# dsa_prep V-transpose loop fully unrolled: 8 loads in flight, counted vmcnt per LDS write group
# speedup vs baseline: 1.0088x; 1.0061x over previous
; __device__ __forceinline__ void dsa_prep(const Args& a, unsigned char* lds, int tid) {
;     ...
;         for (int task = tid; task < 64 * 64; task += NTHREADS) {
;             const int tok = task >> 6, c4 = task & 63;
;             const u32x2 x = *(const u32x2*)(QKVI + (size_t)(t0 + tok) * QKVI_LD + 1280 + 4 * c4);
;             vt[(4 * c4 + 0) * 72 + tok] = (bf16)(x.x & 0xffffu); vt[(4 * c4 + 1) * 72 + tok] = (bf16)(x.x >> 16);
;             vt[(4 * c4 + 2) * 72 + tok] = (bf16)(x.y & 0xffffu); vt[(4 * c4 + 3) * 72 + tok] = (bf16)(x.y >> 16);
;         }
.LBB0_591:
	s_lshl_b32 s6, s23, 6
	s_and_saveexec_b64 s[12:13], s[4:5]
	v_readlane_b32 s26, v248, 61
	v_readlane_b32 s27, v248, 62
	s_cbranch_execz .LBB0_572
	s_mov_b64 s[14:15], 0
	v_mov_b32_e32 v29, v68
	v_mov_b32_e32 v41, v15
	v_ashrrev_i32_e32 v43, 6, v41
	v_add_u32_e32 v46, s6, v43
	v_mov_b64_e32 v[44:45], s[26:27]
	v_and_b32_e32 v48, 0xfc, v29
	v_mad_i64_i32 v[44:45], s[24:25], v46, s22, v[44:45]
	v_lshlrev_b32_e32 v46, 1, v48
	v_mov_b32_e32 v47, v13
	v_lshl_add_u64 v[44:45], v[44:45], 0, v[46:47]
	s_lshl_b32 s14, s22, 3
	s_mov_b32 s15, 0
	global_load_dwordx2 v[100:101], v[44:45], off offset:2560
	v_lshl_add_u64 v[44:45], v[44:45], 0, s[14:15]
	global_load_dwordx2 v[102:103], v[44:45], off offset:2560
	v_lshl_add_u64 v[44:45], v[44:45], 0, s[14:15]
	global_load_dwordx2 v[104:105], v[44:45], off offset:2560
	v_lshl_add_u64 v[44:45], v[44:45], 0, s[14:15]
	global_load_dwordx2 v[106:107], v[44:45], off offset:2560
	v_lshl_add_u64 v[44:45], v[44:45], 0, s[14:15]
	global_load_dwordx2 v[108:109], v[44:45], off offset:2560
	v_lshl_add_u64 v[44:45], v[44:45], 0, s[14:15]
	global_load_dwordx2 v[110:111], v[44:45], off offset:2560
	v_lshl_add_u64 v[44:45], v[44:45], 0, s[14:15]
	global_load_dwordx2 v[112:113], v[44:45], off offset:2560
	v_lshl_add_u64 v[44:45], v[44:45], 0, s[14:15]
	global_load_dwordx2 v[114:115], v[44:45], off offset:2560
	v_mul_u32_u24_e32 v46, 0x90, v48
	v_lshlrev_b32_e32 v43, 1, v43
	v_add3_u32 v43, 0, v46, v43
	s_waitcnt vmcnt(7)
	ds_write_b16 v43, v100 offset:0
	ds_write_b16_d16_hi v43, v100 offset:144
	ds_write_b16 v43, v101 offset:288
	ds_write_b16_d16_hi v43, v101 offset:432
	s_waitcnt vmcnt(6)
	ds_write_b16 v43, v102 offset:16
	ds_write_b16_d16_hi v43, v102 offset:160
	ds_write_b16 v43, v103 offset:304
	ds_write_b16_d16_hi v43, v103 offset:448
	s_waitcnt vmcnt(5)
	ds_write_b16 v43, v104 offset:32
	ds_write_b16_d16_hi v43, v104 offset:176
	ds_write_b16 v43, v105 offset:320
	ds_write_b16_d16_hi v43, v105 offset:464
	s_waitcnt vmcnt(4)
	ds_write_b16 v43, v106 offset:48
	ds_write_b16_d16_hi v43, v106 offset:192
	ds_write_b16 v43, v107 offset:336
	ds_write_b16_d16_hi v43, v107 offset:480
	s_waitcnt vmcnt(3)
	ds_write_b16 v43, v108 offset:64
	ds_write_b16_d16_hi v43, v108 offset:208
	ds_write_b16 v43, v109 offset:352
	ds_write_b16_d16_hi v43, v109 offset:496
	s_waitcnt vmcnt(2)
	ds_write_b16 v43, v110 offset:80
	ds_write_b16_d16_hi v43, v110 offset:224
	ds_write_b16 v43, v111 offset:368
	ds_write_b16_d16_hi v43, v111 offset:512
	s_waitcnt vmcnt(1)
	ds_write_b16 v43, v112 offset:96
	ds_write_b16_d16_hi v43, v112 offset:240
	ds_write_b16 v43, v113 offset:384
	ds_write_b16_d16_hi v43, v113 offset:528
	s_waitcnt vmcnt(0)
	ds_write_b16 v43, v114 offset:112
	ds_write_b16_d16_hi v43, v114 offset:256
	ds_write_b16 v43, v115 offset:400
	ds_write_b16_d16_hi v43, v115 offset:544
	v_add_u32_e32 v41, 0x1000, v15
	v_mov_b32_e32 v43, v41
	v_add_u32_e32 v29, 0x4000, v68
	s_movk_i32 s24, 0xdff
	s_mov_b64 s[14:15], exec
	s_mov_b64 vcc, exec
	s_branch .LBB0_572
